# each GEMM phase starts by touching one 128-B line per thread of its weight matrix (bulk pull from HBM into L2 and MALL) on top of v5
# baseline (speedup 1.0000x reference)
.LBB0_151:
	s_cmp_lt_i32 s58, 2
	s_cselect_b64 s[2:3], -1, 0
	s_add_u32 s36, s56, 0xa000000
	s_addc_u32 s37, s57, 0
	s_and_b64 s[2:3], s[2:3], s[0:1]
	s_andn2_b64 vcc, exec, s[2:3]
	s_cbranch_vccnz .LBB0_168
	v_lshl_add_u32 v255, s30, 9, v196
	v_lshlrev_b32_e32 v255, 7, v255
	s_add_u32 s98, s56, 0x800000
	s_addc_u32 s99, s57, 0
	global_load_dword v255, v255, s[98:99]
	s_cmpk_gt_i32 s30, 0xaff
	v_readfirstlane_b32 s1, v196
	s_cbranch_scc1 .LBB0_168
	v_lshrrev_b32_e32 v2, 1, v196
	v_lshrrev_b32_e32 v3, 5, v196
	v_and_b32_e32 v2, 24, v2
	v_and_b32_e32 v3, 4, v3
	v_bfe_u32 v4, v196, 2, 2
	v_lshlrev_b32_e32 v0, 4, v196
	v_and_b32_e32 v1, 32, v196
	v_bfe_u32 v10, v196, 2, 4
	v_or3_b32 v2, v3, v4, v2
	v_lshrrev_b32_e32 v3, 3, v196
	s_movk_i32 s0, 0x70
	v_bitop3_b32 v8, v0, v1, 48 bitop3:0x6c
	v_and_b32_e32 v9, 64, v196
	v_and_or_b32 v4, v3, s0, v10
	s_movk_i32 s0, 0x60
	v_add_u32_e32 v11, 0x2000, v0
	v_or_b32_e32 v1, v8, v9
	v_and_or_b32 v3, v3, s0, v2
	v_lshrrev_b32_e32 v0, 7, v11
	s_movk_i32 s0, 0xf0
	v_lshl_or_b32 v130, v3, 11, v1
	v_and_or_b32 v3, v0, s0, v10
	s_movk_i32 s0, 0xe0
	s_ashr_i32 s29, s30, 31
	v_and_or_b32 v0, v0, s0, v2
	s_lshr_b32 s0, s29, 29
	s_add_i32 s0, s30, s0
	s_waitcnt lgkmcnt(0)
	s_lshr_b32 s6, s1, 6
	s_ashr_i32 s4, s0, 3
	s_and_b32 s0, s0, -8
	s_lshr_b32 s8, s1, 8
	s_lshl_b32 s28, s6, 10
	s_sub_i32 s0, s30, s0
	s_cmp_lt_i32 s0, 0
	s_movk_i32 s38, 0x161
	s_cselect_b32 s5, s38, 0x160
	s_mul_i32 s0, s0, s5
	s_add_i32 s0, s0, s4
	s_mul_hi_i32 s4, s0, 0x2e8ba2e9
	s_lshr_b32 s5, s4, 31
	s_ashr_i32 s4, s4, 5
	s_add_i32 s4, s4, s5
	s_lshl_b32 s5, s4, 3
	s_mulk_i32 s4, 0xb0
	s_sub_i32 s4, s0, s4
	s_sext_i32_i16 s0, s4
	s_bfe_u32 s0, s0, 0x3001c
	s_add_i32 s7, s4, s0
	s_sext_i32_i16 s0, s7
	s_and_b32 s7, s7, 0xfff8
	s_sub_i32 s4, s4, s7
	s_sext_i32_i16 s4, s4
	s_lshr_b32 s0, s0, 3
	s_add_i32 s18, s5, s4
	s_ashr_i32 s19, s18, 31
	s_bfe_i64 s[10:11], s[0:1], 0x100000
	s_lshl_b64 s[4:5], s[18:19], 19
	s_lshl_b64 s[10:11], s[10:11], 19
	s_add_u32 s24, s68, s10
	s_addc_u32 s25, s69, s11
	s_add_i32 s19, s28, 0
	s_add_i32 m0, s19, 0x10000
	v_lshl_or_b32 v134, v0, 11, v1
	global_load_lds_dwordx4 v130, s[24:25]
	s_add_i32 m0, s19, 0x12000
	s_add_u32 s10, s24, 0x40000
	global_load_lds_dwordx4 v134, s[24:25]
	s_addc_u32 s11, s25, 0
	s_add_i32 m0, s19, 0x14000
	v_lshl_or_b32 v128, v4, 11, v1
	global_load_lds_dwordx4 v130, s[10:11]
	s_add_i32 m0, s19, 0x16000
	s_add_u32 s22, s60, s4
	s_addc_u32 s23, s61, s5
	s_add_i32 s39, s19, 0x2000
	global_load_lds_dwordx4 v134, s[10:11]
	s_mov_b32 m0, s19
	s_add_u32 s4, s22, 0x40000
	v_lshl_or_b32 v132, v3, 11, v1
	global_load_lds_dwordx4 v128, s[22:23]
	s_mov_b32 m0, s39
	s_addc_u32 s5, s23, 0
	s_add_i32 s40, s19, 0x4000
	global_load_lds_dwordx4 v132, s[22:23]
	s_mov_b32 m0, s40
	s_add_i32 s41, s19, 0x6000
	global_load_lds_dwordx4 v128, s[4:5]
	s_mov_b32 m0, s41
	v_mov_b32_e32 v131, 0
	global_load_lds_dwordx4 v132, s[4:5]
	v_mov_b32_e32 v135, v131
	v_mov_b32_e32 v129, v131
	v_mov_b32_e32 v133, v131
	s_cmp_eq_u32 s8, 1
	s_mov_b32 s42, 0
	v_lshl_add_u64 v[6:7], s[24:25], 0, v[130:131]
	v_lshl_add_u64 v[4:5], s[24:25], 0, v[134:135]
	v_lshl_add_u64 v[0:1], s[22:23], 0, v[128:129]
	s_cselect_b64 s[4:5], -1, 0
	s_cmp_lg_u32 s8, 1
	v_lshl_add_u64 v[2:3], s[22:23], 0, v[132:133]
	s_cbranch_scc1 .LBB0_155
	s_barrier

.LBB0_218:
	s_cmp_lt_i32 s58, 3
	s_cselect_b64 s[0:1], -1, 0
	s_and_b64 s[6:7], s[0:1], s[4:5]
	s_andn2_b64 vcc, exec, s[6:7]
	s_cbranch_vccnz .LBB0_261
	v_lshl_add_u32 v255, s30, 9, v196
	v_lshlrev_b32_e32 v255, 7, v255
	s_add_u32 s98, s56, 0x1300000
	s_addc_u32 s99, s57, 0
	global_load_dword v255, v255, s[98:99]
	s_cmpk_lt_i32 s30, 0x200
	s_cselect_b64 s[0:1], -1, 0
	s_cmpk_gt_i32 s30, 0x1ff
	v_readfirstlane_b32 s2, v196
	s_cbranch_scc1 .LBB0_221
	s_ashr_i32 s3, s30, 31
	s_lshr_b32 s3, s3, 29
	s_add_i32 s3, s30, s3
	s_and_b32 s4, s3, -8
	s_sub_i32 s4, s30, s4
	s_lshl_b32 s8, s4, 6
	s_ashr_i32 s3, s3, 3
	s_mul_i32 s5, s4, 0x41
	s_cmp_lt_i32 s4, 0
	s_cselect_b32 s4, s5, s8
	s_add_i32 s3, s4, s3
	s_ashr_i32 s4, s3, 31
	s_lshr_b32 s4, s4, 27
	s_add_i32 s4, s3, s4
	s_ashr_i32 s5, s4, 5
	s_andn2_b32 s4, s4, 31
	s_sub_i32 s3, s3, s4
	s_bfe_i32 s4, s3, 0x80000
	s_bfe_u32 s4, s4, 0x3000c
	s_add_i32 s4, s3, s4
	s_bfe_i32 s8, s4, 0x80000
	s_and_b32 s4, s4, 0xf8
	s_sub_i32 s3, s3, s4
	s_lshl_b32 s5, s5, 3
	s_sext_i32_i16 s8, s8
	s_sext_i32_i8 s3, s3
	s_add_i32 s51, s5, s3
	s_ashr_i32 s8, s8, 3

.LBB0_311:
	s_cmp_lt_i32 s58, 4
	s_cselect_b64 s[2:3], -1, 0
	s_and_b64 s[4:5], s[2:3], s[0:1]
	s_andn2_b64 vcc, exec, s[4:5]
	s_cbranch_vccnz .LBB0_608
	v_lshl_add_u32 v255, s30, 9, v196
	v_lshlrev_b32_e32 v255, 7, v255
	s_add_u32 s98, s56, 0x4a00000
	s_addc_u32 s99, s57, 0
	global_load_dword v255, v255, s[98:99]
	s_cmpk_lt_i32 s30, 0x600
	s_cselect_b64 s[0:1], -1, 0
	s_cmpk_gt_i32 s30, 0x5ff
	v_readfirstlane_b32 s12, v196
	s_cbranch_scc1 .LBB0_314
	s_ashr_i32 s2, s30, 31
	s_lshr_b32 s2, s2, 29
	s_add_i32 s2, s30, s2
	s_ashr_i32 s3, s2, 3
	s_and_b32 s2, s2, -8
	s_sub_i32 s2, s30, s2
	s_cmp_lt_i32 s2, 0
	s_movk_i32 s6, 0xc1
	s_cselect_b32 s6, s6, 0xc0
	s_mul_i32 s2, s2, s6
	s_add_i32 s2, s2, s3
	s_mul_hi_i32 s3, s2, 0x2aaaaaab
	s_lshr_b32 s6, s3, 31
	s_ashr_i32 s3, s3, 4
	s_add_i32 s3, s3, s6
	s_lshl_b32 s6, s3, 3
	s_mulk_i32 s3, 0x60
	s_sub_i32 s2, s2, s3
	s_bfe_i32 s3, s2, 0x80000
	s_bfe_u32 s3, s3, 0x3000c
	s_add_i32 s3, s2, s3
	s_bfe_i32 s7, s3, 0x80000
	s_and_b32 s3, s3, 0xf8
	s_sub_i32 s2, s2, s3
	s_sext_i32_i16 s7, s7
	s_sext_i32_i8 s2, s2
	s_add_i32 s2, s6, s2
	s_ashr_i32 s26, s7, 3

.LBB0_776:
	s_cmp_lt_i32 s58, 6
	s_cselect_b64 s[2:3], -1, 0
	s_and_b64 s[4:5], s[2:3], s[0:1]
	s_andn2_b64 vcc, exec, s[4:5]
	s_cbranch_vccnz .LBB0_819
	v_lshl_add_u32 v255, s30, 9, v196
	v_lshlrev_b32_e32 v255, 7, v255
	s_add_u32 s98, s56, 0x5000000
	s_addc_u32 s99, s57, 0
	global_load_dword v255, v255, s[98:99]
	s_cmpk_lt_i32 s30, 0x200
	s_cselect_b64 s[0:1], -1, 0
	s_cmpk_gt_i32 s30, 0x1ff
	v_readfirstlane_b32 s12, v196
	s_cbranch_scc1 .LBB0_783
	s_ashr_i32 s2, s30, 31
	s_lshr_b32 s2, s2, 29
	s_add_i32 s6, s30, s2
	s_and_b32 s2, s6, -8
	s_sub_i32 s7, s30, s2
	s_cmp_gt_i32 s7, -1
	s_cbranch_scc0 .LBB0_780
	s_lshl_b32 s8, s7, 6
	s_cbranch_execz .LBB0_781
	s_branch .LBB0_782

.LBB0_869:
	s_cmp_lt_i32 s58, 7
	s_cselect_b64 s[2:3], -1, 0
	s_and_b64 s[2:3], s[2:3], s[0:1]
	s_andn2_b64 vcc, exec, s[2:3]
	s_cbranch_vccnz .LBB0_886
	v_lshl_add_u32 v255, s30, 9, v196
	v_lshlrev_b32_e32 v255, 7, v255
	s_add_u32 s98, s56, 0x1880000
	s_addc_u32 s99, s57, 0
	global_load_dword v255, v255, s[98:99]
	s_cmpk_gt_i32 s30, 0xaff
	v_readfirstlane_b32 s1, v196
	s_cbranch_scc1 .LBB0_886
	v_lshrrev_b32_e32 v0, 5, v196
	v_lshrrev_b32_e32 v2, 1, v196
	v_and_b32_e32 v0, 4, v0
	s_waitcnt lgkmcnt(0)
	v_bfe_u32 v1, v196, 2, 2
	v_and_b32_e32 v2, 24, v2
	v_or3_b32 v0, v0, v1, v2
	v_lshlrev_b32_e32 v1, 4, v196
	v_add_u32_e32 v8, 0x2000, v1
	v_lshrrev_b32_e32 v2, 7, v8
	s_movk_i32 s0, 0xe0
	v_and_b32_e32 v4, 32, v196
	v_and_or_b32 v3, v2, s0, v0
	v_bitop3_b32 v9, v1, v4, 48 bitop3:0x6c
	v_and_b32_e32 v10, 64, v196
	v_bfe_u32 v11, v196, 2, 4
	s_movk_i32 s0, 0xf0
	v_or_b32_e32 v1, v9, v10
	v_and_or_b32 v2, v2, s0, v11
	s_add_u32 s28, s56, 0x1880000
	v_lshl_or_b32 v130, v2, 11, v1
	v_lshrrev_b32_e32 v2, 3, v196
	s_movk_i32 s0, 0x60
	s_addc_u32 s29, s57, 0
	v_and_or_b32 v0, v2, s0, v0
	s_movk_i32 s0, 0x70
	s_ashr_i32 s45, s30, 31
	v_lshl_or_b32 v132, v0, 11, v1
	v_and_or_b32 v0, v2, s0, v11
	s_lshr_b32 s0, s45, 29
	s_add_i32 s0, s30, s0
	s_lshr_b32 s6, s1, 6
	s_ashr_i32 s4, s0, 3
	s_and_b32 s0, s0, -8
	s_lshr_b32 s8, s1, 8
	s_lshl_b32 s44, s6, 10
	s_sub_i32 s0, s30, s0
	s_cmp_lt_i32 s0, 0
	s_movk_i32 s46, 0x161
	s_cselect_b32 s5, s46, 0x160
	s_mul_i32 s0, s0, s5
	s_add_i32 s0, s0, s4
	s_mul_hi_i32 s4, s0, 0x2e8ba2e9
	s_lshr_b32 s5, s4, 31
	s_ashr_i32 s4, s4, 5
	s_add_i32 s4, s4, s5
	s_lshl_b32 s5, s4, 3
	s_mulk_i32 s4, 0xb0
	s_sub_i32 s4, s0, s4
	s_sext_i32_i16 s0, s4
	s_bfe_u32 s0, s0, 0x3001c
	s_add_i32 s7, s4, s0
	s_sext_i32_i16 s0, s7
	s_and_b32 s7, s7, 0xfff8
	s_sub_i32 s4, s4, s7
	s_sext_i32_i16 s4, s4
	s_lshr_b32 s0, s0, 3
	s_add_i32 s18, s5, s4
	s_ashr_i32 s19, s18, 31
	s_bfe_i64 s[10:11], s[0:1], 0x100000
	s_lshl_b64 s[4:5], s[18:19], 19
	s_lshl_b64 s[10:11], s[10:11], 19
	s_add_u32 s24, s28, s10
	s_addc_u32 s25, s29, s11
	s_add_i32 s19, s44, 0
	s_add_i32 m0, s19, 0x10000
	v_lshl_or_b32 v128, v3, 11, v1
	global_load_lds_dwordx4 v132, s[24:25]
	s_add_i32 m0, s19, 0x12000
	s_add_u32 s10, s24, 0x40000
	global_load_lds_dwordx4 v128, s[24:25]
	s_addc_u32 s11, s25, 0
	s_add_i32 m0, s19, 0x14000
	v_lshl_or_b32 v134, v0, 11, v1
	global_load_lds_dwordx4 v132, s[10:11]
	s_add_i32 m0, s19, 0x16000
	s_add_u32 s22, s60, s4
	s_addc_u32 s23, s61, s5
	s_add_i32 s47, s19, 0x2000
	global_load_lds_dwordx4 v128, s[10:11]
	s_mov_b32 m0, s19
	s_add_u32 s4, s22, 0x40000
	global_load_lds_dwordx4 v134, s[22:23]
	s_mov_b32 m0, s47
	s_addc_u32 s5, s23, 0
	s_add_i32 s48, s19, 0x4000
	global_load_lds_dwordx4 v130, s[22:23]
	s_mov_b32 m0, s48
	s_add_i32 s49, s19, 0x6000
	global_load_lds_dwordx4 v134, s[4:5]
	s_mov_b32 m0, s49
	v_mov_b32_e32 v133, 0
	global_load_lds_dwordx4 v130, s[4:5]
	v_mov_b32_e32 v129, v133
	v_mov_b32_e32 v135, v133
	v_mov_b32_e32 v131, v133
	s_cmp_eq_u32 s8, 1
	s_mov_b32 s50, 0
	v_lshl_add_u64 v[6:7], s[24:25], 0, v[132:133]
	v_lshl_add_u64 v[4:5], s[24:25], 0, v[128:129]
	v_lshl_add_u64 v[0:1], s[22:23], 0, v[134:135]
	s_cselect_b64 s[4:5], -1, 0
	s_cmp_lg_u32 s8, 1
	v_lshl_add_u64 v[2:3], s[22:23], 0, v[130:131]
	s_cbranch_scc1 .LBB0_873
	s_barrier

.LBB0_936:
	s_cmp_lt_i32 s58, 8
	s_cselect_b64 s[2:3], -1, 0
	s_and_b64 s[6:7], s[2:3], s[0:1]
	s_andn2_b64 vcc, exec, s[6:7]
	s_cbranch_vccnz .LBB0_983
	v_lshl_add_u32 v255, s30, 9, v196
	v_lshlrev_b32_e32 v255, 7, v255
	s_add_u32 s98, s56, 0x2380000
	s_addc_u32 s99, s57, 0
	global_load_dword v255, v255, s[98:99]
	s_cmpk_lt_i32 s30, 0x200
	s_cselect_b64 s[0:1], -1, 0
	s_cmpk_gt_i32 s30, 0x1ff
	v_readfirstlane_b32 s4, v196
	s_cbranch_scc1 .LBB0_943
	s_ashr_i32 s2, s30, 31
	s_lshr_b32 s2, s2, 29
	s_add_i32 s5, s30, s2
	s_and_b32 s2, s5, -8
	s_sub_i32 s8, s30, s2
	s_cmp_gt_i32 s8, -1
	s_cbranch_scc0 .LBB0_940
	s_lshl_b32 s9, s8, 6
	s_cbranch_execz .LBB0_941
	s_branch .LBB0_942

.LBB0_1033:
	s_cmp_lt_i32 s58, 9
	s_cselect_b64 s[2:3], -1, 0
	s_add_u32 s6, s56, 0x200000
	s_addc_u32 s7, s57, 0
	s_and_b64 s[8:9], s[2:3], s[0:1]
	s_andn2_b64 vcc, exec, s[8:9]
	s_cbranch_vccnz .LBB0_1364
	v_lshl_add_u32 v255, s30, 9, v196
	v_lshlrev_b32_e32 v255, 7, v255
	s_add_u32 s98, s56, 0x5200000
	s_addc_u32 s99, s57, 0
	global_load_dword v254, v255, s[98:99]
	s_add_u32 s98, s56, 0x2900000
	s_addc_u32 s99, s57, 0
	global_load_dword v255, v255, s[98:99]
	s_cmpk_lt_i32 s30, 0x400
	s_cselect_b64 s[0:1], -1, 0
	s_cmpk_gt_i32 s30, 0x3ff
	v_readfirstlane_b32 s16, v196
	s_cbranch_scc1 .LBB0_1040
	s_ashr_i32 s2, s30, 31
	s_lshr_b32 s2, s2, 29
	s_add_i32 s4, s30, s2
	s_and_b32 s2, s4, -8
	s_sub_i32 s5, s30, s2
	s_cmp_gt_i32 s5, -1
	s_cbranch_scc0 .LBB0_1037
	s_lshl_b32 s10, s5, 7
	s_cbranch_execz .LBB0_1038
	s_branch .LBB0_1039

.LBB0_1414:
	s_cmp_lt_i32 s58, 10
	s_cselect_b64 s[2:3], -1, 0
	s_and_b64 s[8:9], s[2:3], s[0:1]
	s_andn2_b64 vcc, exec, s[8:9]
	s_cbranch_vccnz .LBB0_1461
	v_lshl_add_u32 v255, s30, 9, v196
	v_lshlrev_b32_e32 v255, 7, v255
	s_add_u32 s98, s56, 0x3400000
	s_addc_u32 s99, s57, 0
	global_load_dword v255, v255, s[98:99]
	s_cmpk_lt_i32 s30, 0x200
	s_cselect_b64 s[0:1], -1, 0
	s_cmpk_gt_i32 s30, 0x1ff
	v_readfirstlane_b32 s4, v196
	s_cbranch_scc1 .LBB0_1421
	s_ashr_i32 s2, s30, 31
	s_lshr_b32 s2, s2, 29
	s_add_i32 s5, s30, s2
	s_and_b32 s2, s5, -8
	s_sub_i32 s10, s30, s2
	s_cmp_gt_i32 s10, -1
	s_cbranch_scc0 .LBB0_1418
	s_lshl_b32 s11, s10, 6
	s_cbranch_execz .LBB0_1419
	s_branch .LBB0_1420

.LBB0_1511:
	s_cmp_lt_i32 s58, 11
	s_cselect_b64 s[2:3], -1, 0
	s_and_b64 s[8:9], s[2:3], s[0:1]
	s_andn2_b64 vcc, exec, s[8:9]
	s_cbranch_vccnz .LBB0_1819
	v_lshl_add_u32 v255, s30, 9, v196
	v_lshlrev_b32_e32 v255, 7, v255
	s_add_u32 s98, s56, 0x5600000
	s_addc_u32 s99, s57, 0
	global_load_dword v255, v255, s[98:99]
	v_lshl_add_u32 v0, s30, 9, v196
	s_mov_b32 s0, 0x20000
	v_cmp_gt_i32_e32 vcc, s0, v0
	s_and_saveexec_b64 s[0:1], vcc
	s_cbranch_execz .LBB0_1515
	s_lshl_b32 s2, s31, 9
	s_waitcnt lgkmcnt(0)
	v_ashrrev_i32_e32 v1, 31, v0
	v_lshl_add_u64 v[2:3], v[0:1], 2, s[56:57]
	s_mov_b64 s[4:5], 0x300000
	s_ashr_i32 s3, s2, 31
	v_lshl_add_u64 v[2:3], v[2:3], 0, s[4:5]
	s_lshl_b64 s[4:5], s[2:3], 2
	s_mov_b64 s[10:11], 0
	v_mov_b32_e32 v5, 0
	s_mov_b32 s3, 0x1ffff

.LBB0_2020:
	s_cmp_lt_i32 s58, 13
	s_cselect_b64 s[2:3], -1, 0
	s_and_b64 s[4:5], s[2:3], s[0:1]
	s_andn2_b64 vcc, exec, s[4:5]
	s_cbranch_vccnz .LBB0_2063
	v_lshl_add_u32 v255, s30, 9, v196
	v_lshlrev_b32_e32 v255, 7, v255
	s_add_u32 s98, s56, 0x5800000
	s_addc_u32 s99, s57, 0
	global_load_dword v255, v255, s[98:99]
	s_cmpk_lt_i32 s30, 0x200
	s_cselect_b64 s[0:1], -1, 0
	s_cmpk_gt_i32 s30, 0x1ff
	v_readfirstlane_b32 s12, v196
	s_cbranch_scc1 .LBB0_2027
	s_ashr_i32 s2, s30, 31
	s_lshr_b32 s2, s2, 29
	s_add_i32 s6, s30, s2
	s_and_b32 s2, s6, -8
	s_sub_i32 s7, s30, s2
	s_cmp_gt_i32 s7, -1
	s_cbranch_scc0 .LBB0_2024
	s_lshl_b32 s8, s7, 6
	s_cbranch_execz .LBB0_2025
	s_branch .LBB0_2026

.LBB0_2113:
	s_cmp_lt_i32 s58, 14
	s_cselect_b64 s[2:3], -1, 0
	s_and_b64 s[2:3], s[2:3], s[0:1]
	s_andn2_b64 vcc, exec, s[2:3]
	s_cbranch_vccnz .LBB0_2130
	v_lshl_add_u32 v255, s30, 9, v196
	v_lshlrev_b32_e32 v255, 7, v255
	s_add_u32 s98, s56, 0x3980000
	s_addc_u32 s99, s57, 0
	global_load_dword v255, v255, s[98:99]
	s_cmpk_gt_i32 s30, 0xaff
	v_readfirstlane_b32 s1, v196
	s_cbranch_scc1 .LBB0_2130
	v_lshrrev_b32_e32 v0, 5, v196
	s_waitcnt lgkmcnt(0)
	v_lshrrev_b32_e32 v2, 1, v196
	v_and_b32_e32 v0, 4, v0
	v_bfe_u32 v1, v196, 2, 2
	v_and_b32_e32 v2, 24, v2
	v_or3_b32 v0, v0, v1, v2
	v_lshlrev_b32_e32 v1, 4, v196
	v_add_u32_e32 v8, 0x2000, v1
	v_lshrrev_b32_e32 v2, 7, v8
	s_movk_i32 s0, 0xe0
	v_and_b32_e32 v4, 32, v196
	v_and_or_b32 v3, v2, s0, v0
	v_bitop3_b32 v9, v1, v4, 48 bitop3:0x6c
	v_and_b32_e32 v10, 64, v196
	v_bfe_u32 v11, v196, 2, 4
	s_movk_i32 s0, 0xf0
	v_or_b32_e32 v1, v9, v10
	v_and_or_b32 v2, v2, s0, v11
	s_add_u32 s26, s56, 0x3980000
	v_lshl_or_b32 v130, v2, 11, v1
	v_lshrrev_b32_e32 v2, 3, v196
	s_movk_i32 s0, 0x60
	s_addc_u32 s27, s57, 0
	v_and_or_b32 v0, v2, s0, v0
	s_movk_i32 s0, 0x70
	s_ashr_i32 s29, s30, 31
	v_lshl_or_b32 v132, v0, 11, v1
	v_and_or_b32 v0, v2, s0, v11
	s_lshr_b32 s0, s29, 29
	s_add_i32 s0, s30, s0
	s_lshr_b32 s6, s1, 6
	s_ashr_i32 s4, s0, 3
	s_and_b32 s0, s0, -8
	s_lshr_b32 s8, s1, 8
	s_lshl_b32 s28, s6, 10
	s_sub_i32 s0, s30, s0
	s_cmp_lt_i32 s0, 0
	s_movk_i32 s38, 0x161
	s_cselect_b32 s5, s38, 0x160
	s_mul_i32 s0, s0, s5
	s_add_i32 s0, s0, s4
	s_mul_hi_i32 s4, s0, 0x2e8ba2e9
	s_lshr_b32 s5, s4, 31
	s_ashr_i32 s4, s4, 5
	s_add_i32 s4, s4, s5
	s_lshl_b32 s5, s4, 3
	s_mulk_i32 s4, 0xb0
	s_sub_i32 s4, s0, s4
	s_sext_i32_i16 s0, s4
	s_bfe_u32 s0, s0, 0x3001c
	s_add_i32 s7, s4, s0
	s_sext_i32_i16 s0, s7
	s_and_b32 s7, s7, 0xfff8
	s_sub_i32 s4, s4, s7
	s_sext_i32_i16 s4, s4
	s_lshr_b32 s0, s0, 3
	s_add_i32 s18, s5, s4
	s_ashr_i32 s19, s18, 31
	s_bfe_i64 s[10:11], s[0:1], 0x100000
	s_lshl_b64 s[4:5], s[18:19], 19
	s_lshl_b64 s[10:11], s[10:11], 19
	s_add_u32 s22, s26, s10
	s_addc_u32 s23, s27, s11
	s_add_i32 s19, s28, 0
	s_add_i32 m0, s19, 0x10000
	v_lshl_or_b32 v128, v3, 11, v1
	global_load_lds_dwordx4 v132, s[22:23]
	s_add_i32 m0, s19, 0x12000
	s_add_u32 s10, s22, 0x40000
	global_load_lds_dwordx4 v128, s[22:23]
	s_addc_u32 s11, s23, 0
	s_add_i32 m0, s19, 0x14000
	v_lshl_or_b32 v134, v0, 11, v1
	global_load_lds_dwordx4 v132, s[10:11]
	s_add_i32 m0, s19, 0x16000
	s_add_u32 s20, s60, s4
	s_addc_u32 s21, s61, s5
	s_add_i32 s39, s19, 0x2000
	global_load_lds_dwordx4 v128, s[10:11]
	s_mov_b32 m0, s19
	s_add_u32 s4, s20, 0x40000
	global_load_lds_dwordx4 v134, s[20:21]
	s_mov_b32 m0, s39
	s_addc_u32 s5, s21, 0
	s_add_i32 s40, s19, 0x4000
	global_load_lds_dwordx4 v130, s[20:21]
	s_mov_b32 m0, s40
	s_add_i32 s41, s19, 0x6000
	global_load_lds_dwordx4 v134, s[4:5]
	s_mov_b32 m0, s41
	v_mov_b32_e32 v133, 0
	global_load_lds_dwordx4 v130, s[4:5]
	v_mov_b32_e32 v129, v133
	v_mov_b32_e32 v135, v133
	v_mov_b32_e32 v131, v133
	s_cmp_eq_u32 s8, 1
	s_mov_b32 s42, 0
	v_lshl_add_u64 v[6:7], s[22:23], 0, v[132:133]
	v_lshl_add_u64 v[4:5], s[22:23], 0, v[128:129]
	v_lshl_add_u64 v[0:1], s[20:21], 0, v[134:135]
	s_cselect_b64 s[4:5], -1, 0
	s_cmp_lg_u32 s8, 1
	v_lshl_add_u64 v[2:3], s[20:21], 0, v[130:131]
	s_cbranch_scc1 .LBB0_2117
	s_barrier

.LBB0_2180:
	s_cmp_lt_i32 s58, 15
	s_cselect_b64 s[2:3], -1, 0
	s_and_b64 s[6:7], s[2:3], s[0:1]
	s_andn2_b64 vcc, exec, s[6:7]
	s_cbranch_vccnz .LBB0_2227
	v_lshl_add_u32 v255, s30, 9, v196
	v_lshlrev_b32_e32 v255, 7, v255
	s_add_u32 s98, s56, 0x4480000
	s_addc_u32 s99, s57, 0
	global_load_dword v255, v255, s[98:99]
	s_cmpk_lt_i32 s30, 0x200
	s_cselect_b64 s[0:1], -1, 0
	s_cmpk_gt_i32 s30, 0x1ff
	v_readfirstlane_b32 s4, v196
	s_cbranch_scc1 .LBB0_2187
	s_ashr_i32 s2, s30, 31
	s_lshr_b32 s2, s2, 29
	s_add_i32 s9, s30, s2
	s_and_b32 s2, s9, -8
	s_sub_i32 s5, s30, s2
	s_cmp_gt_i32 s5, -1
	s_cbranch_scc0 .LBB0_2184
	s_lshl_b32 s8, s5, 6
	s_ashr_i32 s2, s9, 3
	s_cbranch_execz .LBB0_2185
	s_branch .LBB0_2186

	.amdhsa_kernel _Z10fwd_kernel4Args
		.amdhsa_group_segment_fixed_size 0
		.amdhsa_private_segment_fixed_size 0
		.amdhsa_kernarg_size 416
		.amdhsa_user_sgpr_count 2
		.amdhsa_user_sgpr_dispatch_ptr 0
		.amdhsa_user_sgpr_queue_ptr 0
		.amdhsa_user_sgpr_kernarg_segment_ptr 1
		.amdhsa_user_sgpr_dispatch_id 0
		.amdhsa_user_sgpr_kernarg_preload_length 0
		.amdhsa_user_sgpr_kernarg_preload_offset 0
		.amdhsa_user_sgpr_private_segment_size 0
		.amdhsa_uses_dynamic_stack 0
		.amdhsa_enable_private_segment 0
		.amdhsa_system_sgpr_workgroup_id_x 1
		.amdhsa_system_sgpr_workgroup_id_y 0
		.amdhsa_system_sgpr_workgroup_id_z 0
		.amdhsa_system_sgpr_workgroup_info 0
		.amdhsa_system_vgpr_workitem_id 2
		.amdhsa_next_free_vgpr 256
		.amdhsa_next_free_sgpr 102
		.amdhsa_accum_offset 256
		.amdhsa_reserve_vcc 1
		.amdhsa_float_round_mode_32 0
		.amdhsa_float_round_mode_16_64 0
		.amdhsa_float_denorm_mode_32 3
		.amdhsa_float_denorm_mode_16_64 3
		.amdhsa_dx10_clamp 1
		.amdhsa_ieee_mode 1
		.amdhsa_fp16_overflow 0
		.amdhsa_tg_split 0
		.amdhsa_exception_fp_ieee_invalid_op 0
		.amdhsa_exception_fp_denorm_src 0
		.amdhsa_exception_fp_ieee_div_zero 0
		.amdhsa_exception_fp_ieee_overflow 0
		.amdhsa_exception_fp_ieee_underflow 0
		.amdhsa_exception_fp_ieee_inexact 0
		.amdhsa_exception_int_div_zero 0
	.end_amdhsa_kernel

amdhsa.kernels:
  - .agpr_count:     0
    .args:
      - .offset:         0
        .size:           160
        .value_kind:     by_value
      - .offset:         160
        .size:           4
        .value_kind:     hidden_block_count_x
      - .offset:         164
        .size:           4
        .value_kind:     hidden_block_count_y
      - .offset:         168
        .size:           4
        .value_kind:     hidden_block_count_z
      - .offset:         172
        .size:           2
        .value_kind:     hidden_group_size_x
      - .offset:         174
        .size:           2
        .value_kind:     hidden_group_size_y
      - .offset:         176
        .size:           2
        .value_kind:     hidden_group_size_z
      - .offset:         178
        .size:           2
        .value_kind:     hidden_remainder_x
      - .offset:         180
        .size:           2
        .value_kind:     hidden_remainder_y
      - .offset:         182
        .size:           2
        .value_kind:     hidden_remainder_z
      - .offset:         200
        .size:           8
        .value_kind:     hidden_global_offset_x
      - .offset:         208
        .size:           8
        .value_kind:     hidden_global_offset_y
      - .offset:         216
        .size:           8
        .value_kind:     hidden_global_offset_z
      - .offset:         224
        .size:           2
        .value_kind:     hidden_grid_dims
      - .offset:         248
        .size:           8
        .value_kind:     hidden_multigrid_sync_arg
      - .offset:         280
        .size:           4
        .value_kind:     hidden_dynamic_lds_size
    .group_segment_fixed_size: 0
    .kernarg_segment_align: 8
    .kernarg_segment_size: 416
    .language:       OpenCL C
    .language_version:
      - 2
      - 0
    .max_flat_workgroup_size: 512
    .name:           _Z10fwd_kernel4Args
    .private_segment_fixed_size: 0
    .sgpr_count:     108
    .sgpr_spill_count: 2
    .symbol:         _Z10fwd_kernel4Args.kd
    .uniform_work_group_size: 1
    .uses_dynamic_stack: false
    .vgpr_count:     256
    .vgpr_spill_count: 0
    .wavefront_size: 64
